# phase-U GEMM loops: first MFMA-only wave L2-prefetches the per-workgroup A-operand slab 3 K-tiles beyond the DMA front
# baseline (speedup 1.0000x reference)
; DI f32x4 mfma16(bf16x8 a, bf16x8 b, f32x4 c) { return __builtin_amdgcn_mfma_f32_16x16x32_bf16(a, b, c, 0, 0, 0); }
; template <int N> DI void wait_vm() { asm volatile("s_waitcnt vmcnt(%0)" ::"n"(N) : "memory"); }
; DI void raw_barrier() { asm volatile("" ::: "memory"); __builtin_amdgcn_s_barrier(); asm volatile("" ::: "memory"); }
;     ...
;     auto compute = [&](int cb, bool do_issue, int ikt, int ib) {
;         const char* base = lds + cb * BUF;
;         bf16x8 af[MT], bfr[NT];
; #pragma unroll
;         for (int nt = 0; nt < NT; ++nt) {
;             const int br = BM + (nt / NTS) * (BN / NSEG) + wc * (NTS * 16) + (nt % NTS) * 16;
;             bfr[nt] = *(const bf16x8*)(base + (br + l15) * 64 + rsw);
;         }
; #pragma unroll
;         for (int mt = 0; mt < MT; ++mt) af[mt] = *(const bf16x8*)(base + (wr * WM + mt * 16 + l15) * 64 + rsw);
;         constexpr int TOT = MT * NT, PER = (TOT + NIT - 1) / NIT;
; #pragma unroll
;         for (int part = 0; part < NIT; ++part) {
; #pragma unroll
;             for (int q = 0; q < PER; ++q) {
;                 const int idx = part * PER + q;
;                 if (idx < TOT) {
;                     const int mt = idx / NT, nt = idx % NT;
;                     acc[mt][nt] = SWAP ? mfma16(bfr[nt], af[mt], acc[mt][nt]) : mfma16(af[mt], bfr[nt], acc[mt][nt]);
;                 }
;             }
;             __builtin_amdgcn_sched_barrier(0);
;             if (do_issue) issue_one(ikt, ib, part);
;             __builtin_amdgcn_sched_barrier(0);
;         }
;     };
;     __syncthreads();
; #pragma unroll
;     for (int d = 0; d < D; ++d) issue(d, d);
;     int cb = 0, ib = D;
;     for (int kt = 0; kt < KT; ++kt) {
;         if (D > 1 && kt + D - 1 < KT) wait_vm<(D - 1) * NIT>(); else wait_vm<0>();
;         raw_barrier();
;         compute(cb, kt + D < KT, kt + D, ib);
;         cb = (cb + 1 == NST) ? 0 : cb + 1;
;         ib = (ib + 1 == NST) ? 0 : ib + 1;
;     }
.Lpx_c_entry:
	s_add_i32 s0, s0, 2
	s_mov_b32 s6, 1
	v_readfirstlane_b32 s96, v130
	v_readfirstlane_b32 s97, v131
	v_readfirstlane_b32 s94, v0
	s_nop 3
	s_sub_u32 s96, s96, s94
	s_subb_u32 s97, s97, 0
	s_sub_u32 s95, s9, 0x100
	s_lshr_b32 s95, s95, 6
	v_and_b32_e32 v229, 63, v212
	v_lshlrev_b32_e32 v229, 7, v229
	s_waitcnt vmcnt(0)
	s_cmp_lg_u32 s95, 0
	s_cbranch_scc1 .Lpx_npf_e0
	s_add_i32 s94, s59, 6
	s_and_b32 s94, s94, 62
	s_lshl_b32 s94, s94, 12
	s_add_u32 s92, s96, s94
	s_addc_u32 s93, s97, 0
	global_load_dword v228, v229, s[92:93]
.Lpx_npf_e0:
	s_cmp_lg_u32 s95, 0
	s_cbranch_scc1 .Lpx_npf_e1
	s_add_i32 s94, s59, 8
	s_and_b32 s94, s94, 62
	s_lshl_b32 s94, s94, 12
	s_add_u32 s92, s96, s94
	s_addc_u32 s93, s97, 0
	global_load_dword v228, v229, s[92:93]
.Lpx_npf_e1:
	s_cmp_lg_u32 s95, 0
	s_cbranch_scc1 .Lpx_npf_e2
	s_add_i32 s94, s59, 10
	s_and_b32 s94, s94, 62
	s_lshl_b32 s94, s94, 12
	s_add_u32 s92, s96, s94
	s_addc_u32 s93, s97, 0
	global_load_dword v228, v229, s[92:93]
.Lpx_npf_e2:
	s_barrier
	v_add_u32_e32 v225, v135, v138
	v_add_u32_e32 v224, v135, v136
	ds_read_b128 v[144:147], v224
	ds_read_b128 v[152:155], v224 offset:1024
	ds_read_b128 v[180:183], v224 offset:2048
	ds_read_b128 v[140:143], v225 offset:8192
	ds_read_b128 v[148:151], v225 offset:9216
	ds_read_b128 v[156:159], v225 offset:10240
	ds_read_b128 v[160:163], v225 offset:11264
	ds_read_b128 v[164:167], v225 offset:12288
	ds_read_b128 v[168:171], v225 offset:13312
	ds_read_b128 v[172:175], v225 offset:14336
	ds_read_b128 v[176:179], v225 offset:15360
	ds_read_b128 v[184:187], v224 offset:3072
.Lpx_c_loop:
	s_mul_i32 s9, s6, 0xa000
	v_add_u32_e32 v226, s9, v135
	v_add_u32_e32 v225, v226, v138
	v_add_u32_e32 v224, v226, v136
	s_waitcnt lgkmcnt(8)
	v_mfma_f32_16x16x32_bf16 v[126:129], v[140:143], v[144:147], v[126:129]
	s_waitcnt lgkmcnt(7)
	v_mfma_f32_16x16x32_bf16 v[122:125], v[148:151], v[144:147], v[122:125]
	s_waitcnt lgkmcnt(6)
	v_mfma_f32_16x16x32_bf16 v[118:121], v[156:159], v[144:147], v[118:121]
	s_waitcnt lgkmcnt(5)
	v_mfma_f32_16x16x32_bf16 v[114:117], v[160:163], v[144:147], v[114:117]
	s_waitcnt lgkmcnt(4)
	v_mfma_f32_16x16x32_bf16 v[110:113], v[164:167], v[144:147], v[110:113]
	s_waitcnt lgkmcnt(3)
	v_mfma_f32_16x16x32_bf16 v[106:109], v[168:171], v[144:147], v[106:109]
	s_waitcnt lgkmcnt(2)
	v_mfma_f32_16x16x32_bf16 v[102:105], v[172:175], v[144:147], v[102:105]
	s_waitcnt lgkmcnt(1)
	v_mfma_f32_16x16x32_bf16 v[98:101], v[176:179], v[144:147], v[98:101]
	s_waitcnt lgkmcnt(0)
	s_barrier
	ds_read_b128 v[144:147], v224
	s_cmp_lg_u32 s95, 0
	s_cbranch_scc1 .Lpx_npf_skip
	s_add_i32 s94, s59, s0
	s_add_i32 s94, s94, 6
	s_and_b32 s94, s94, 62
	s_lshl_b32 s94, s94, 12
	s_add_u32 s92, s96, s94
	s_addc_u32 s93, s97, 0
	global_load_dword v228, v229, s[92:93]
; DI f32x4 mfma16(bf16x8 a, bf16x8 b, f32x4 c) { return __builtin_amdgcn_mfma_f32_16x16x32_bf16(a, b, c, 0, 0, 0); }
; template <int N> DI void wait_vm() { asm volatile("s_waitcnt vmcnt(%0)" ::"n"(N) : "memory"); }
; DI void raw_barrier() { asm volatile("" ::: "memory"); __builtin_amdgcn_s_barrier(); asm volatile("" ::: "memory"); }
;     ...
;     auto compute = [&](int cb, bool do_issue, int ikt, int ib) {
;         const char* base = lds + cb * BUF;
;         bf16x8 af[MT], bfr[NT];
; #pragma unroll
;         for (int nt = 0; nt < NT; ++nt) {
;             const int br = BM + (nt / NTS) * (BN / NSEG) + wc * (NTS * 16) + (nt % NTS) * 16;
;             bfr[nt] = *(const bf16x8*)(base + (br + l15) * 64 + rsw);
;         }
; #pragma unroll
;         for (int mt = 0; mt < MT; ++mt) af[mt] = *(const bf16x8*)(base + (wr * WM + mt * 16 + l15) * 64 + rsw);
;         constexpr int TOT = MT * NT, PER = (TOT + NIT - 1) / NIT;
; #pragma unroll
;         for (int part = 0; part < NIT; ++part) {
; #pragma unroll
;             for (int q = 0; q < PER; ++q) {
;                 const int idx = part * PER + q;
;                 if (idx < TOT) {
;                     const int mt = idx / NT, nt = idx % NT;
;                     acc[mt][nt] = SWAP ? mfma16(bfr[nt], af[mt], acc[mt][nt]) : mfma16(af[mt], bfr[nt], acc[mt][nt]);
;                 }
;             }
;             __builtin_amdgcn_sched_barrier(0);
;             if (do_issue) issue_one(ikt, ib, part);
;             __builtin_amdgcn_sched_barrier(0);
;         }
;     };
;     __syncthreads();
; #pragma unroll
;     for (int d = 0; d < D; ++d) issue(d, d);
;     int cb = 0, ib = D;
;     for (int kt = 0; kt < KT; ++kt) {
;         if (D > 1 && kt + D - 1 < KT) wait_vm<(D - 1) * NIT>(); else wait_vm<0>();
;         raw_barrier();
;         compute(cb, kt + D < KT, kt + D, ib);
;         cb = (cb + 1 == NST) ? 0 : cb + 1;
;         ib = (ib + 1 == NST) ? 0 : ib + 1;
;     }
.Lpx_npf_skip:
	v_mfma_f32_16x16x32_bf16 v[94:97], v[140:143], v[152:155], v[94:97]
	v_mfma_f32_16x16x32_bf16 v[90:93], v[148:151], v[152:155], v[90:93]
	v_mfma_f32_16x16x32_bf16 v[86:89], v[156:159], v[152:155], v[86:89]
	v_mfma_f32_16x16x32_bf16 v[82:85], v[160:163], v[152:155], v[82:85]
	v_mfma_f32_16x16x32_bf16 v[78:81], v[164:167], v[152:155], v[78:81]
	v_mfma_f32_16x16x32_bf16 v[74:77], v[168:171], v[152:155], v[74:77]
	v_mfma_f32_16x16x32_bf16 v[70:73], v[172:175], v[152:155], v[70:73]
	v_mfma_f32_16x16x32_bf16 v[66:69], v[176:179], v[152:155], v[66:69]
	ds_read_b128 v[152:155], v224 offset:1024
	v_mfma_f32_16x16x32_bf16 v[62:65], v[140:143], v[180:183], v[62:65]
	v_mfma_f32_16x16x32_bf16 v[58:61], v[148:151], v[180:183], v[58:61]
	v_mfma_f32_16x16x32_bf16 v[54:57], v[156:159], v[180:183], v[54:57]
	v_mfma_f32_16x16x32_bf16 v[50:53], v[160:163], v[180:183], v[50:53]
	v_mfma_f32_16x16x32_bf16 v[46:49], v[164:167], v[180:183], v[46:49]
	v_mfma_f32_16x16x32_bf16 v[42:45], v[168:171], v[180:183], v[42:45]
	v_mfma_f32_16x16x32_bf16 v[38:41], v[172:175], v[180:183], v[38:41]
	v_mfma_f32_16x16x32_bf16 v[34:37], v[176:179], v[180:183], v[34:37]
	ds_read_b128 v[180:183], v224 offset:2048
	v_mfma_f32_16x16x32_bf16 v[30:33], v[140:143], v[184:187], v[30:33]
	ds_read_b128 v[140:143], v225 offset:8192
	v_mfma_f32_16x16x32_bf16 v[26:29], v[148:151], v[184:187], v[26:29]
	ds_read_b128 v[148:151], v225 offset:9216
	v_mfma_f32_16x16x32_bf16 v[22:25], v[156:159], v[184:187], v[22:25]
	ds_read_b128 v[156:159], v225 offset:10240
	v_mfma_f32_16x16x32_bf16 v[18:21], v[160:163], v[184:187], v[18:21]
	ds_read_b128 v[160:163], v225 offset:11264
	v_mfma_f32_16x16x32_bf16 v[14:17], v[164:167], v[184:187], v[14:17]
	ds_read_b128 v[164:167], v225 offset:12288
	v_mfma_f32_16x16x32_bf16 v[10:13], v[168:171], v[184:187], v[10:13]
	ds_read_b128 v[168:171], v225 offset:13312
	v_mfma_f32_16x16x32_bf16 v[6:9], v[172:175], v[184:187], v[6:9]
	ds_read_b128 v[172:175], v225 offset:14336
	v_mfma_f32_16x16x32_bf16 v[2:5], v[176:179], v[184:187], v[2:5]
	ds_read_b128 v[176:179], v225 offset:15360
	ds_read_b128 v[184:187], v224 offset:3072
	s_add_i32 s6, s6, 1
	s_cmp_lg_u32 s6, 3
	s_cselect_b32 s6, s6, 0
	s_add_i32 s0, s0, 2
	s_cmp_lg_u32 s0, 64
	s_cbranch_scc1 .Lpx_c_loop
	s_waitcnt lgkmcnt(8)
	v_mfma_f32_16x16x32_bf16 v[126:129], v[140:143], v[144:147], v[126:129]
	s_waitcnt lgkmcnt(7)
	v_mfma_f32_16x16x32_bf16 v[122:125], v[148:151], v[144:147], v[122:125]
	s_waitcnt lgkmcnt(6)
	v_mfma_f32_16x16x32_bf16 v[118:121], v[156:159], v[144:147], v[118:121]
	s_waitcnt lgkmcnt(5)
	v_mfma_f32_16x16x32_bf16 v[114:117], v[160:163], v[144:147], v[114:117]
	s_waitcnt lgkmcnt(4)
	v_mfma_f32_16x16x32_bf16 v[110:113], v[164:167], v[144:147], v[110:113]
	s_waitcnt lgkmcnt(3)
	v_mfma_f32_16x16x32_bf16 v[106:109], v[168:171], v[144:147], v[106:109]
	s_waitcnt lgkmcnt(2)
	v_mfma_f32_16x16x32_bf16 v[102:105], v[172:175], v[144:147], v[102:105]
	s_waitcnt lgkmcnt(1)
	v_mfma_f32_16x16x32_bf16 v[98:101], v[176:179], v[144:147], v[98:101]
	s_waitcnt lgkmcnt(0)
	v_mfma_f32_16x16x32_bf16 v[94:97], v[140:143], v[152:155], v[94:97]
	v_mfma_f32_16x16x32_bf16 v[90:93], v[148:151], v[152:155], v[90:93]
	v_mfma_f32_16x16x32_bf16 v[86:89], v[156:159], v[152:155], v[86:89]
	v_mfma_f32_16x16x32_bf16 v[82:85], v[160:163], v[152:155], v[82:85]
	v_mfma_f32_16x16x32_bf16 v[78:81], v[164:167], v[152:155], v[78:81]
	v_mfma_f32_16x16x32_bf16 v[74:77], v[168:171], v[152:155], v[74:77]
	v_mfma_f32_16x16x32_bf16 v[70:73], v[172:175], v[152:155], v[70:73]
	v_mfma_f32_16x16x32_bf16 v[66:69], v[176:179], v[152:155], v[66:69]
	v_mfma_f32_16x16x32_bf16 v[62:65], v[140:143], v[180:183], v[62:65]
	v_mfma_f32_16x16x32_bf16 v[58:61], v[148:151], v[180:183], v[58:61]
	v_mfma_f32_16x16x32_bf16 v[54:57], v[156:159], v[180:183], v[54:57]
	v_mfma_f32_16x16x32_bf16 v[50:53], v[160:163], v[180:183], v[50:53]
	v_mfma_f32_16x16x32_bf16 v[46:49], v[164:167], v[180:183], v[46:49]
	v_mfma_f32_16x16x32_bf16 v[42:45], v[168:171], v[180:183], v[42:45]
	v_mfma_f32_16x16x32_bf16 v[38:41], v[172:175], v[180:183], v[38:41]
	v_mfma_f32_16x16x32_bf16 v[34:37], v[176:179], v[180:183], v[34:37]
	v_mfma_f32_16x16x32_bf16 v[30:33], v[140:143], v[184:187], v[30:33]
	v_mfma_f32_16x16x32_bf16 v[26:29], v[148:151], v[184:187], v[26:29]
	v_mfma_f32_16x16x32_bf16 v[22:25], v[156:159], v[184:187], v[22:25]
	v_mfma_f32_16x16x32_bf16 v[18:21], v[160:163], v[184:187], v[18:21]
	v_mfma_f32_16x16x32_bf16 v[14:17], v[164:167], v[184:187], v[14:17]
	v_mfma_f32_16x16x32_bf16 v[10:13], v[168:171], v[184:187], v[10:13]
	v_mfma_f32_16x16x32_bf16 v[6:9], v[172:175], v[184:187], v[6:9]
	v_mfma_f32_16x16x32_bf16 v[2:5], v[176:179], v[184:187], v[2:5]

; template <int N> DI void wait_vm() { asm volatile("s_waitcnt vmcnt(%0)" ::"n"(N) : "memory"); }
; DI void raw_barrier() { asm volatile("" ::: "memory"); __builtin_amdgcn_s_barrier(); asm volatile("" ::: "memory"); }
;     ...
;     __syncthreads();
; #pragma unroll
;     for (int d = 0; d < D; ++d) issue(d, d);
;     int cb = 0, ib = D;
;     for (int kt = 0; kt < KT; ++kt) {
;         if (D > 1 && kt + D - 1 < KT) wait_vm<(D - 1) * NIT>(); else wait_vm<0>();
;         raw_barrier();
;         compute(cb, kt + D < KT, kt + D, ib);
.Lpa_c_entry:
	s_add_i32 s7, s7, 2
	s_mov_b32 s12, 1
	v_readfirstlane_b32 s96, v98
	v_readfirstlane_b32 s97, v99
	v_readfirstlane_b32 s94, v0
	s_nop 3
	s_sub_u32 s96, s96, s94
	s_subb_u32 s97, s97, 0
	s_sub_u32 s95, s40, 0x100
	s_lshr_b32 s95, s95, 6
	v_and_b32_e32 v229, 63, v212
	v_lshlrev_b32_e32 v229, 7, v229
	s_waitcnt vmcnt(0)
	s_cmp_lg_u32 s95, 0
	s_cbranch_scc1 .Lpa_npf_e0
	s_add_i32 s94, s59, 6
	s_and_b32 s94, s94, 62
	s_lshl_b32 s94, s94, 12
	s_add_u32 s92, s96, s94
	s_addc_u32 s93, s97, 0
	global_load_dword v228, v229, s[92:93]

; DI f32x4 mfma16(bf16x8 a, bf16x8 b, f32x4 c) { return __builtin_amdgcn_mfma_f32_16x16x32_bf16(a, b, c, 0, 0, 0); }
; template <int N> DI void wait_vm() { asm volatile("s_waitcnt vmcnt(%0)" ::"n"(N) : "memory"); }
; DI void raw_barrier() { asm volatile("" ::: "memory"); __builtin_amdgcn_s_barrier(); asm volatile("" ::: "memory"); }
;     ...
;     auto compute = [&](int cb, bool do_issue, int ikt, int ib) {
;         const char* base = lds + cb * BUF;
;         bf16x8 af[MT], bfr[NT];
; #pragma unroll
;         for (int nt = 0; nt < NT; ++nt) {
;             const int br = BM + (nt / NTS) * (BN / NSEG) + wc * (NTS * 16) + (nt % NTS) * 16;
;             bfr[nt] = *(const bf16x8*)(base + (br + l15) * 64 + rsw);
;         }
; #pragma unroll
;         for (int mt = 0; mt < MT; ++mt) af[mt] = *(const bf16x8*)(base + (wr * WM + mt * 16 + l15) * 64 + rsw);
;         constexpr int TOT = MT * NT, PER = (TOT + NIT - 1) / NIT;
; #pragma unroll
;         for (int part = 0; part < NIT; ++part) {
; #pragma unroll
;             for (int q = 0; q < PER; ++q) {
;                 const int idx = part * PER + q;
;                 if (idx < TOT) {
;                     const int mt = idx / NT, nt = idx % NT;
;                     acc[mt][nt] = SWAP ? mfma16(bfr[nt], af[mt], acc[mt][nt]) : mfma16(af[mt], bfr[nt], acc[mt][nt]);
;                 }
;             }
;             __builtin_amdgcn_sched_barrier(0);
;             if (do_issue) issue_one(ikt, ib, part);
;             __builtin_amdgcn_sched_barrier(0);
;         }
;     };
;     __syncthreads();
; #pragma unroll
;     for (int d = 0; d < D; ++d) issue(d, d);
;     int cb = 0, ib = D;
;     for (int kt = 0; kt < KT; ++kt) {
;         if (D > 1 && kt + D - 1 < KT) wait_vm<(D - 1) * NIT>(); else wait_vm<0>();
;         raw_barrier();
;         compute(cb, kt + D < KT, kt + D, ib);
;         cb = (cb + 1 == NST) ? 0 : cb + 1;
;         ib = (ib + 1 == NST) ? 0 : ib + 1;
;     }
.Lpa_npf_e2:
	s_barrier
	v_add_u32_e32 v225, v103, v104
	v_add_u32_e32 v224, v103, v105
	ds_read_b128 v[106:109], v224
	ds_read_b128 v[118:121], v224 offset:1024
	ds_read_b128 v[138:141], v224 offset:2048
	ds_read_b128 v[110:113], v225 offset:8192
	ds_read_b128 v[114:117], v225 offset:9216
	ds_read_b128 v[122:125], v225 offset:16384
	ds_read_b128 v[126:129], v225 offset:17408
	ds_read_b128 v[130:133], v225 offset:24576
	ds_read_b128 v[134:137], v225 offset:25600
	ds_read_b128 v[142:145], v224 offset:3072
.Lpa_c_loop:
	s_mul_i32 s40, s12, 0x8000
	v_add_u32_e32 v226, s40, v103
	v_add_u32_e32 v225, v226, v104
	v_add_u32_e32 v224, v226, v105
	s_waitcnt lgkmcnt(6)
	v_mfma_f32_16x16x32_bf16 v[94:97], v[106:109], v[110:113], v[94:97]
	s_waitcnt lgkmcnt(5)
	v_mfma_f32_16x16x32_bf16 v[90:93], v[106:109], v[114:117], v[90:93]
	s_waitcnt lgkmcnt(4)
	v_mfma_f32_16x16x32_bf16 v[86:89], v[106:109], v[122:125], v[86:89]
	s_waitcnt lgkmcnt(3)
	v_mfma_f32_16x16x32_bf16 v[82:85], v[106:109], v[126:129], v[82:85]
	s_waitcnt lgkmcnt(2)
	v_mfma_f32_16x16x32_bf16 v[78:81], v[106:109], v[130:133], v[78:81]
	s_waitcnt lgkmcnt(1)
	v_mfma_f32_16x16x32_bf16 v[74:77], v[106:109], v[134:137], v[74:77]
	s_waitcnt lgkmcnt(0)
	s_barrier
	ds_read_b128 v[106:109], v224
	s_cmp_lg_u32 s95, 0
	s_cbranch_scc1 .Lpa_npf_skip
	s_add_i32 s94, s59, s7
	s_add_i32 s94, s94, 6
	s_and_b32 s94, s94, 62
	s_lshl_b32 s94, s94, 12
	s_add_u32 s92, s96, s94
	s_addc_u32 s93, s97, 0
	global_load_dword v228, v229, s[92:93]
.Lpa_npf_skip:
	v_mfma_f32_16x16x32_bf16 v[70:73], v[118:121], v[110:113], v[70:73]
	v_mfma_f32_16x16x32_bf16 v[66:69], v[118:121], v[114:117], v[66:69]
	v_mfma_f32_16x16x32_bf16 v[62:65], v[118:121], v[122:125], v[62:65]
	v_mfma_f32_16x16x32_bf16 v[58:61], v[118:121], v[126:129], v[58:61]
	v_mfma_f32_16x16x32_bf16 v[54:57], v[118:121], v[130:133], v[54:57]
	v_mfma_f32_16x16x32_bf16 v[50:53], v[118:121], v[134:137], v[50:53]
	ds_read_b128 v[118:121], v224 offset:1024
	v_mfma_f32_16x16x32_bf16 v[46:49], v[138:141], v[110:113], v[46:49]
	v_mfma_f32_16x16x32_bf16 v[42:45], v[138:141], v[114:117], v[42:45]
	v_mfma_f32_16x16x32_bf16 v[38:41], v[138:141], v[122:125], v[38:41]
	v_mfma_f32_16x16x32_bf16 v[34:37], v[138:141], v[126:129], v[34:37]
	v_mfma_f32_16x16x32_bf16 v[30:33], v[138:141], v[130:133], v[30:33]
	v_mfma_f32_16x16x32_bf16 v[26:29], v[138:141], v[134:137], v[26:29]
	ds_read_b128 v[138:141], v224 offset:2048
	v_mfma_f32_16x16x32_bf16 v[22:25], v[142:145], v[110:113], v[22:25]
	ds_read_b128 v[110:113], v225 offset:8192
	v_mfma_f32_16x16x32_bf16 v[18:21], v[142:145], v[114:117], v[18:21]
	ds_read_b128 v[114:117], v225 offset:9216
	v_mfma_f32_16x16x32_bf16 v[14:17], v[142:145], v[122:125], v[14:17]
	ds_read_b128 v[122:125], v225 offset:16384
	v_mfma_f32_16x16x32_bf16 v[10:13], v[142:145], v[126:129], v[10:13]
	ds_read_b128 v[126:129], v225 offset:17408
	v_mfma_f32_16x16x32_bf16 v[6:9], v[142:145], v[130:133], v[6:9]
	ds_read_b128 v[130:133], v225 offset:24576
	v_mfma_f32_16x16x32_bf16 v[2:5], v[142:145], v[134:137], v[2:5]
	ds_read_b128 v[134:137], v225 offset:25600
	ds_read_b128 v[142:145], v224 offset:3072
	s_add_i32 s12, s12, 1
	s_cmp_lg_u32 s12, 3
	s_cselect_b32 s12, s12, 0
	s_add_i32 s7, s7, 2
	s_cmp_lg_u32 s7, 64
	s_cbranch_scc1 .Lpa_c_loop
	s_waitcnt lgkmcnt(6)
	v_mfma_f32_16x16x32_bf16 v[94:97], v[106:109], v[110:113], v[94:97]
	s_waitcnt lgkmcnt(5)
	v_mfma_f32_16x16x32_bf16 v[90:93], v[106:109], v[114:117], v[90:93]
	s_waitcnt lgkmcnt(4)
	v_mfma_f32_16x16x32_bf16 v[86:89], v[106:109], v[122:125], v[86:89]
	s_waitcnt lgkmcnt(3)
	v_mfma_f32_16x16x32_bf16 v[82:85], v[106:109], v[126:129], v[82:85]
	s_waitcnt lgkmcnt(2)
	v_mfma_f32_16x16x32_bf16 v[78:81], v[106:109], v[130:133], v[78:81]
	s_waitcnt lgkmcnt(1)
	v_mfma_f32_16x16x32_bf16 v[74:77], v[106:109], v[134:137], v[74:77]
	s_waitcnt lgkmcnt(0)
	v_mfma_f32_16x16x32_bf16 v[70:73], v[118:121], v[110:113], v[70:73]
	v_mfma_f32_16x16x32_bf16 v[66:69], v[118:121], v[114:117], v[66:69]
	v_mfma_f32_16x16x32_bf16 v[62:65], v[118:121], v[122:125], v[62:65]
	v_mfma_f32_16x16x32_bf16 v[58:61], v[118:121], v[126:129], v[58:61]
	v_mfma_f32_16x16x32_bf16 v[54:57], v[118:121], v[130:133], v[54:57]
	v_mfma_f32_16x16x32_bf16 v[50:53], v[118:121], v[134:137], v[50:53]
	v_mfma_f32_16x16x32_bf16 v[46:49], v[138:141], v[110:113], v[46:49]
	v_mfma_f32_16x16x32_bf16 v[42:45], v[138:141], v[114:117], v[42:45]
	v_mfma_f32_16x16x32_bf16 v[38:41], v[138:141], v[122:125], v[38:41]
	v_mfma_f32_16x16x32_bf16 v[34:37], v[138:141], v[126:129], v[34:37]
	v_mfma_f32_16x16x32_bf16 v[30:33], v[138:141], v[130:133], v[30:33]
	v_mfma_f32_16x16x32_bf16 v[26:29], v[138:141], v[134:137], v[26:29]
	v_mfma_f32_16x16x32_bf16 v[22:25], v[142:145], v[110:113], v[22:25]
	v_mfma_f32_16x16x32_bf16 v[18:21], v[142:145], v[114:117], v[18:21]
	v_mfma_f32_16x16x32_bf16 v[14:17], v[142:145], v[122:125], v[14:17]
	v_mfma_f32_16x16x32_bf16 v[10:13], v[142:145], v[126:129], v[10:13]
	v_mfma_f32_16x16x32_bf16 v[6:9], v[142:145], v[130:133], v[6:9]
	v_mfma_f32_16x16x32_bf16 v[2:5], v[142:145], v[134:137], v[2:5]

; template <int N> DI void wait_vm() { asm volatile("s_waitcnt vmcnt(%0)" ::"n"(N) : "memory"); }
; DI void raw_barrier() { asm volatile("" ::: "memory"); __builtin_amdgcn_s_barrier(); asm volatile("" ::: "memory"); }
;     ...
;     __syncthreads();
; #pragma unroll
;     for (int d = 0; d < D; ++d) issue(d, d);
;     int cb = 0, ib = D;
;     for (int kt = 0; kt < KT; ++kt) {
;         if (D > 1 && kt + D - 1 < KT) wait_vm<(D - 1) * NIT>(); else wait_vm<0>();
;         raw_barrier();
;         compute(cb, kt + D < KT, kt + D, ib);
.Lpb1_c_entry:
	s_add_i32 s0, s0, 2
	s_mov_b32 s6, 1
	v_readfirstlane_b32 s96, v130
	v_readfirstlane_b32 s97, v131
	v_readfirstlane_b32 s94, v0
	s_nop 3
	s_sub_u32 s96, s96, s94
	s_subb_u32 s97, s97, 0
	s_sub_u32 s95, s40, 0x100
	s_lshr_b32 s95, s95, 6
	v_and_b32_e32 v229, 63, v212
	v_lshlrev_b32_e32 v229, 7, v229
	s_waitcnt vmcnt(0)
	s_cmp_lg_u32 s95, 0
	s_cbranch_scc1 .Lpb1_npf_e0
	s_add_i32 s94, s59, 6
	s_and_b32 s94, s94, 62
	s_lshl_b32 s94, s94, 12
	s_add_u32 s92, s96, s94
	s_addc_u32 s93, s97, 0
	global_load_dword v228, v229, s[92:93]

; DI f32x4 mfma16(bf16x8 a, bf16x8 b, f32x4 c) { return __builtin_amdgcn_mfma_f32_16x16x32_bf16(a, b, c, 0, 0, 0); }
; template <int N> DI void wait_vm() { asm volatile("s_waitcnt vmcnt(%0)" ::"n"(N) : "memory"); }
; DI void raw_barrier() { asm volatile("" ::: "memory"); __builtin_amdgcn_s_barrier(); asm volatile("" ::: "memory"); }
;     ...
;     auto compute = [&](int cb, bool do_issue, int ikt, int ib) {
;         const char* base = lds + cb * BUF;
;         bf16x8 af[MT], bfr[NT];
; #pragma unroll
;         for (int nt = 0; nt < NT; ++nt) {
;             const int br = BM + (nt / NTS) * (BN / NSEG) + wc * (NTS * 16) + (nt % NTS) * 16;
;             bfr[nt] = *(const bf16x8*)(base + (br + l15) * 64 + rsw);
;         }
; #pragma unroll
;         for (int mt = 0; mt < MT; ++mt) af[mt] = *(const bf16x8*)(base + (wr * WM + mt * 16 + l15) * 64 + rsw);
;         constexpr int TOT = MT * NT, PER = (TOT + NIT - 1) / NIT;
; #pragma unroll
;         for (int part = 0; part < NIT; ++part) {
; #pragma unroll
;             for (int q = 0; q < PER; ++q) {
;                 const int idx = part * PER + q;
;                 if (idx < TOT) {
;                     const int mt = idx / NT, nt = idx % NT;
;                     acc[mt][nt] = SWAP ? mfma16(bfr[nt], af[mt], acc[mt][nt]) : mfma16(af[mt], bfr[nt], acc[mt][nt]);
;                 }
;             }
;             __builtin_amdgcn_sched_barrier(0);
;             if (do_issue) issue_one(ikt, ib, part);
;             __builtin_amdgcn_sched_barrier(0);
;         }
;     };
;     __syncthreads();
; #pragma unroll
;     for (int d = 0; d < D; ++d) issue(d, d);
;     int cb = 0, ib = D;
;     for (int kt = 0; kt < KT; ++kt) {
;         if (D > 1 && kt + D - 1 < KT) wait_vm<(D - 1) * NIT>(); else wait_vm<0>();
;         raw_barrier();
;         compute(cb, kt + D < KT, kt + D, ib);
;         cb = (cb + 1 == NST) ? 0 : cb + 1;
;         ib = (ib + 1 == NST) ? 0 : ib + 1;
;     }
.Lpb1_npf_e2:
	s_barrier
	v_add_u32_e32 v225, v136, v138
	v_add_u32_e32 v224, v136, v137
	ds_read_b128 v[144:147], v224
	ds_read_b128 v[152:155], v224 offset:1024
	ds_read_b128 v[180:183], v224 offset:2048
	ds_read_b128 v[140:143], v225 offset:8192
	ds_read_b128 v[148:151], v225 offset:9216
	ds_read_b128 v[156:159], v225 offset:10240
	ds_read_b128 v[160:163], v225 offset:11264
	ds_read_b128 v[164:167], v225 offset:12288
	ds_read_b128 v[168:171], v225 offset:13312
	ds_read_b128 v[172:175], v225 offset:14336
	ds_read_b128 v[176:179], v225 offset:15360
	ds_read_b128 v[184:187], v224 offset:3072
.Lpb1_c_loop:
	s_mul_i32 s40, s6, 0xa000
	v_add_u32_e32 v226, s40, v136
	v_add_u32_e32 v225, v226, v138
	v_add_u32_e32 v224, v226, v137
	s_waitcnt lgkmcnt(8)
	v_mfma_f32_16x16x32_bf16 v[126:129], v[140:143], v[144:147], v[126:129]
	s_waitcnt lgkmcnt(7)
	v_mfma_f32_16x16x32_bf16 v[122:125], v[148:151], v[144:147], v[122:125]
	s_waitcnt lgkmcnt(6)
	v_mfma_f32_16x16x32_bf16 v[118:121], v[156:159], v[144:147], v[118:121]
	s_waitcnt lgkmcnt(5)
	v_mfma_f32_16x16x32_bf16 v[114:117], v[160:163], v[144:147], v[114:117]
	s_waitcnt lgkmcnt(4)
	v_mfma_f32_16x16x32_bf16 v[110:113], v[164:167], v[144:147], v[110:113]
	s_waitcnt lgkmcnt(3)
	v_mfma_f32_16x16x32_bf16 v[106:109], v[168:171], v[144:147], v[106:109]
	s_waitcnt lgkmcnt(2)
	v_mfma_f32_16x16x32_bf16 v[102:105], v[172:175], v[144:147], v[102:105]
	s_waitcnt lgkmcnt(1)
	v_mfma_f32_16x16x32_bf16 v[98:101], v[176:179], v[144:147], v[98:101]
	s_waitcnt lgkmcnt(0)
	s_barrier
	ds_read_b128 v[144:147], v224
	s_cmp_lg_u32 s95, 0
	s_cbranch_scc1 .Lpb1_npf_skip
	s_add_i32 s94, s59, s0
	s_add_i32 s94, s94, 6
	s_and_b32 s94, s94, 62
	s_lshl_b32 s94, s94, 12
	s_add_u32 s92, s96, s94
	s_addc_u32 s93, s97, 0
	global_load_dword v228, v229, s[92:93]
